# adds phase-2 heterogeneous order: half of the workgroups run the chunk tasks before the memory-bound branch-A conv
# baseline (speedup 1.0000x reference)
.LBB0_354:
	s_cmp_gt_i32 s84, 2
	s_cselect_b64 s[4:5], -1, 0
	s_cmp_lt_i32 s85, 3
	s_cselect_b64 s[6:7], -1, 0
	s_or_b64 s[4:5], s[4:5], s[6:7]
	s_and_b64 vcc, exec, s[4:5]
	s_cbranch_vccnz .LBB0_820
	s_mov_b32 s98, 0
	s_bitcmp1_b32 s2, 3
	s_cbranch_scc0 .Lmy_p2_conv
	s_mov_b32 s98, 1
	s_branch .Lmy_p2_chunk
.Lmy_p2_conv:
	v_mov_b32_e32 v0, v170
	s_movk_i32 s3, 0x840
	v_ashrrev_i32_e32 v24, 7, v0
	v_lshl_add_u32 v121, s2, 2, v24
	v_cmp_gt_i32_e32 vcc, s3, v121
	s_and_saveexec_b64 s[4:5], vcc
	s_cbranch_execz .LBB0_414
	s_waitcnt lgkmcnt(0)
	s_load_dwordx2 s[10:11], s[0:1], 0x30
	s_load_dwordx2 s[6:7], s[0:1], 0x80
	v_lshlrev_b32_e32 v0, 3, v0
	v_and_b32_e32 v120, 0x3f8, v0
	v_mov_b32_e32 v123, 0
	v_lshlrev_b32_e32 v122, 2, v120
	s_waitcnt lgkmcnt(0)
	v_lshl_add_u64 v[8:9], s[10:11], 0, v[122:123]
	s_movk_i32 s3, 0x2000
	v_add_co_u32_e32 v30, vcc, s3, v8
	s_mov_b64 s[8:9], 0x1000
	s_mov_b64 s[12:13], 0x2000
	v_addc_co_u32_e32 v31, vcc, 0, v9, vcc
	s_waitcnt vmcnt(0)
	v_lshl_add_u64 v[26:27], v[8:9], 0, s[8:9]
	v_lshl_add_u64 v[28:29], v[8:9], 0, s[12:13]
	global_load_dwordx4 v[0:3], v122, s[10:11] offset:16
	global_load_dwordx4 v[4:7], v122, s[10:11]
	global_load_dwordx4 v[8:11], v[30:31], off offset:-4096
	global_load_dwordx4 v[12:15], v[30:31], off
	global_load_dwordx4 v[16:19], v[26:27], off offset:16
	global_load_dwordx4 v[20:23], v[28:29], off offset:16
	s_load_dwordx2 s[10:11], s[0:1], 0xf8
	s_load_dwordx2 s[12:13], s[0:1], 0x10
	s_load_dwordx2 s[14:15], s[0:1], 0x98
	s_lshl_b32 s3, s30, 2
	v_lshlrev_b32_e32 v26, 1, v120
	v_mov_b32_e32 v27, v123
	s_waitcnt lgkmcnt(0)
	v_lshl_add_u64 v[124:125], s[10:11], 0, v[26:27]
	s_add_u32 s10, s6, 0x4658000
	s_addc_u32 s11, s7, 0
	v_lshl_add_u64 v[128:129], s[12:13], 0, v[122:123]
	s_add_u32 s12, s6, 0x4200000
	v_lshl_add_u64 v[126:127], s[14:15], 0, v[26:27]
	s_addc_u32 s13, s7, 0
	s_lshl_b32 s14, s2, 5
	v_lshlrev_b32_e32 v24, 3, v24
	v_lshl_add_u64 v[130:131], s[10:11], 0, v[122:123]
	v_add3_u32 v122, s14, v24, -2
	s_lshl_b32 s24, s30, 5
	s_mov_b64 s[14:15], 0
	s_movk_i32 s25, 0x7ff
	s_movk_i32 s26, 0x3fff
	s_movk_i32 s27, 0x7fe
	s_movk_i32 s28, 0x7fd
	s_movk_i32 s29, 0x83f
	s_branch .LBB0_358

.LBB0_414:
	s_or_b64 exec, exec, s[4:5]
	s_cmp_eq_u32 s98, 2
	s_cbranch_scc1 .LBB0_770
.Lmy_p2_chunk:
	s_cmpk_lt_i32 s2, 0x800
	v_mov_b32_e32 v88, v170
	s_cselect_b64 s[4:5], -1, 0
	s_ashr_i32 s3, s2, 3
	s_load_dwordx2 s[74:75], s[0:1], 0x100
	s_load_dwordx2 s[48:49], s[0:1], 0x88
	s_lshl_b32 s18, s3, 6
	s_add_i32 s18, s18, -3
	s_and_b32 s6, s2, 0xf8
	v_mov_b32_e32 v48, 0
	s_cmp_lg_u32 s6, 0
	s_mulk_i32 s3, 0xffc3
	s_waitcnt lgkmcnt(0)
	s_movk_i32 s10, 0xc90
	v_mov_b32_e32 v50, v48
	v_mov_b32_e32 v51, v48
	s_cselect_b64 s[8:9], -1, 0
	s_add_i32 s6, s18, s3
	s_lshl_b32 s3, s2, 7
	v_cmp_gt_i32_e32 vcc, s10, v88
	v_mov_b32_e32 v49, v48
	v_mov_b64_e32 v[54:55], v[50:51]
	s_ashr_i32 s7, s6, 31
	s_and_b32 s3, s3, 0x380
	s_and_b64 s[12:13], s[4:5], vcc
	v_mov_b64_e32 v[52:53], v[48:49]
	s_and_saveexec_b64 s[10:11], s[12:13]
	s_cbranch_execz .LBB0_425
	s_mov_b32 s12, 0x2aaaaaab
	v_mul_hi_i32 v0, v88, s12
	v_lshrrev_b32_e32 v1, 31, v0
	v_ashrrev_i32_e32 v0, 3, v0
	v_add_u32_e32 v2, v0, v1
	v_mul_lo_u32 v0, v2, 48
	v_sub_u32_e32 v4, v88, v0
	s_movk_i32 s12, 0x8f
	v_ashrrev_i32_e32 v5, 4, v4
	v_cmp_lt_i32_e32 vcc, s12, v88
	s_mov_b64 s[12:13], 0
	s_and_saveexec_b64 s[14:15], vcc
	s_xor_b64 s[14:15], exec, s[14:15]
	v_add_u32_e32 v2, s18, v2
	s_movk_i32 s16, 0x1800
	v_mov_b64_e32 v[0:1], s[48:49]
	v_mad_i64_i32 v[0:1], s[16:17], v2, s16, v[0:1]
	v_lshlrev_b32_e32 v2, 11, v5
	v_mov_b32_e32 v3, 0
	s_mov_b64 s[12:13], exec
	v_lshl_add_u64 v[0:1], v[0:1], 0, v[2:3]
	s_andn2_saveexec_b64 s[14:15], s[14:15]
	s_cbranch_execz .LBB0_422
	s_and_b64 vcc, exec, s[8:9]
	s_cbranch_vccz .LBB0_420
	v_ashrrev_i32_e32 v3, 31, v2
	v_lshl_add_u64 v[0:1], v[2:3], 0, s[6:7]
	s_movk_i32 s19, 0x1800
	v_mov_b64_e32 v[2:3], s[74:75]
	v_mad_u64_u32 v[2:3], s[16:17], v0, s19, v[2:3]
	v_lshlrev_b32_e32 v0, 10, v5
	v_mad_i32_i24 v3, v1, s19, v3
	v_ashrrev_i32_e32 v1, 31, v0
	v_lshl_add_u64 v[0:1], v[0:1], 1, v[2:3]
	s_or_b64 s[16:17], s[12:13], exec
	s_branch .LBB0_421

.LBB0_770:
	s_waitcnt lgkmcnt(0)
	s_cmp_lg_u32 s98, 1
	s_cbranch_scc1 .Lmy_p2_end
	s_mov_b32 s98, 2
	s_branch .Lmy_p2_conv
.Lmy_p2_end:
	s_cmp_lt_i32 s85, 4
	s_cbranch_scc1 .LBB0_820
	s_waitcnt vmcnt(0)
	v_cmp_eq_u32_e32 vcc, 0, v170
	s_waitcnt vmcnt(0)
	s_barrier
	s_and_saveexec_b64 s[4:5], vcc
	s_cbranch_execz .LBB0_819
	s_add_i32 s3, 0, 0x25a00
	v_mov_b32_e32 v0, s3
	s_waitcnt vmcnt(0) expcnt(0) lgkmcnt(0)
	ds_read_b32 v2, v0
	s_add_i32 s3, 0, 0x25a04
	v_mov_b32_e32 v0, s3
	ds_read_b32 v0, v0
	s_waitcnt lgkmcnt(1)
	v_cmp_ne_u32_e32 vcc, 0, v2
	s_cbranch_vccnz .LBB0_787
	s_add_u32 s6, s44, 0x1000
	s_addc_u32 s7, s45, 0
	s_add_u32 s8, s44, 0x1100
	s_addc_u32 s9, s45, 0
	s_add_u32 s10, s44, 0x1200
	s_addc_u32 s11, s45, 0
	s_mul_i32 s3, s31, s87
	s_add_u32 s12, s44, 0x1300
	s_mul_i32 s3, s3, s30
	s_addc_u32 s13, s45, 0
	s_mov_b32 s20, 1
	v_mov_b32_e32 v16, 0
	s_branch .LBB0_775
